# MLA half-1 row sums deferred into next tile's QK phase; MLA barrier 4 MFMAs later; diff staging writes issued earlier
# baseline (speedup 1.0000x reference)
; #define SBAR() __builtin_amdgcn_sched_barrier(0)
; __device__ __forceinline__ void attn_diff1(const bf16* __restrict__ Qrow, const bf16* __restrict__ Kn, const bf16* __restrict__ Vh, const int* __restrict__ posk, const float pq, const float cneg, ...
;     ...
;         {   const char* kb = buf + KN_OFF + r32 * 144 + hi * 16;
;             bf16x8 c0 = *reinterpret_cast<const bf16x8*>(kb), c1 = *reinterpret_cast<const bf16x8*>(kb + 32 * 144);
; #pragma unroll
;             for (int d0 = 0; d0 < 4; ++d0) {
;                 bf16x8 n0 = c0, n1 = c1;
;                 if (d0 + 1 < 4) { n0 = *reinterpret_cast<const bf16x8*>(kb + (d0 + 1) * 32); n1 = *reinterpret_cast<const bf16x8*>(kb + 32 * 144 + (d0 + 1) * 32); }
;                 p0 = __builtin_amdgcn_mfma_f32_32x32x16_bf16(c0, qr[d0], p0, 0, 0, 0); p1 = __builtin_amdgcn_mfma_f32_32x32x16_bf16(c1, qr[d0], p1, 0, 0, 0);
;                 c0 = n0; c1 = n1;
;             }
;         }
;         if (t + 1 < NT) SLOADD((t0 + t + 1) * 64);
;         const int vb = vb0 + cur;
;     ...
;         s16x4 la[4], ha[4], lb[4], hb[4];
;         VRD(0, la, ha); VRD(1, lb, hb);
;         {   const char* pkl = buf + PK_OFF;
; #pragma unroll
;             for (int i = 0; i < 4; ++i) {
;                 const f32x4 k0 = *(const f32x4*)(pkl + (8 * i + 4 * hi) * 4), k1 = *(const f32x4*)(pkl + (32 + 8 * i + 4 * hi) * 4);
; #pragma unroll
;                 for (int q = 0; q < 4; ++q) { p0[4 * i + q] = fmaf(fabsf(pq - k0[q]), cneg, p0[4 * i + q]); p1[4 * i + q] = fmaf(fabsf(pq - k1[q]), cneg, p1[4 * i + q]); }
;             }
;         }
;         bf16x8 fa0, fa1, fa2, fa3;
;         {   float ps = 0.f;
; #pragma unroll
;             for (int r = 0; r < 16; ++r) { p0[r] = __builtin_amdgcn_exp2f(p0[r]); p1[r] = __builtin_amdgcn_exp2f(p1[r]);     ps += p0[r] + p1[r]; }
;             l_reg += ps; PK4(p0, 0, fa0); PK4(p0, 8, fa1); PK4(p1, 0, fa2); PK4(p1, 8, fa3); }
;         asm volatile("s_waitcnt lgkmcnt(0)" ::: "memory"); SBAR();
;         PVM(0, la, ha); SBAR();
;         VRD(2, la, ha);
;         SBAR(); PVM(1, lb, hb); SBAR();
;         VRD(3, lb, hb);
;         asm volatile("s_waitcnt lgkmcnt(8)" ::: "memory"); SBAR();
;         PVM(2, la, ha);
;         asm volatile("s_waitcnt lgkmcnt(0)" ::: "memory"); SBAR();
;         PVM(3, lb, hb);
;     ...
;         if (t + 1 < NT) SWRITED(BUF - cur);
.Ld1_skipld:
	v_and_b32_e32 v209, 32, v241
	v_mad_u32_u24 v209, v209, 56, v228
	v_add_u32_e32 v209, s45, v209
	s_waitcnt lgkmcnt(11)
	v_mfma_f32_32x32x16_bf16 v[64:79], v[124:127], v[96:99], 0
	s_waitcnt lgkmcnt(10)
	v_mfma_f32_32x32x16_bf16 v[64:79], v[128:131], v[100:103], v[64:79]
	s_waitcnt lgkmcnt(9)
	v_mfma_f32_32x32x16_bf16 v[64:79], v[132:135], v[112:115], v[64:79]
	s_waitcnt lgkmcnt(8)
	v_mfma_f32_32x32x16_bf16 v[64:79], v[136:139], v[116:119], v[64:79]
	ds_read_b64_tr_b16 v[124:125], v209
	ds_read_b64_tr_b16 v[126:127], v209 offset:256
	ds_read_b64_tr_b16 v[128:129], v209 offset:512
	ds_read_b64_tr_b16 v[130:131], v209 offset:768
	ds_read_b64_tr_b16 v[132:133], v209 offset:1024
	ds_read_b64_tr_b16 v[134:135], v209 offset:1280
	ds_read_b64_tr_b16 v[136:137], v209 offset:1536
	ds_read_b64_tr_b16 v[138:139], v209 offset:1792
	s_waitcnt lgkmcnt(8)
	v_sub_f32_e32 v186, v168, v186
	v_sub_f32_e32 v187, v168, v187
	v_sub_f32_e32 v188, v168, v188
	v_sub_f32_e32 v189, v168, v189
	s_waitcnt lgkmcnt(15)
	v_mfma_f32_32x32x16_bf16 v[80:95], v[140:143], v[96:99], 0
	v_sub_f32_e32 v230, v168, v230
	v_sub_f32_e32 v231, v168, v231
	v_sub_f32_e32 v232, v168, v232
	v_sub_f32_e32 v233, v168, v233
	s_waitcnt lgkmcnt(14)
	v_mfma_f32_32x32x16_bf16 v[80:95], v[144:147], v[100:103], v[80:95]
	v_sub_f32_e32 v234, v168, v234
	v_sub_f32_e32 v235, v168, v235
	v_sub_f32_e32 v236, v168, v236
	v_sub_f32_e32 v237, v168, v237
	s_waitcnt lgkmcnt(13)
	v_mfma_f32_32x32x16_bf16 v[80:95], v[148:151], v[112:115], v[80:95]
	v_sub_f32_e32 v242, v168, v242
	v_sub_f32_e32 v243, v168, v243
	v_sub_f32_e32 v244, v168, v244
	v_sub_f32_e32 v245, v168, v245
	s_waitcnt lgkmcnt(12)
	v_mfma_f32_32x32x16_bf16 v[80:95], v[152:155], v[116:119], v[80:95]
	ds_read_b64_tr_b16 v[140:141], v209 offset:4096
	ds_read_b64_tr_b16 v[142:143], v209 offset:4352
	ds_read_b64_tr_b16 v[144:145], v209 offset:4608
	ds_read_b64_tr_b16 v[146:147], v209 offset:4864
	ds_read_b64_tr_b16 v[148:149], v209 offset:5120
	ds_read_b64_tr_b16 v[150:151], v209 offset:5376
	ds_read_b64_tr_b16 v[152:153], v209 offset:5632
	ds_read_b64_tr_b16 v[154:155], v209 offset:5888
	v_fma_f32 v64, |v186|, -v165, v64
	v_fma_f32 v65, |v187|, -v165, v65
	v_fma_f32 v66, |v188|, -v165, v66
	v_fma_f32 v67, |v189|, -v165, v67
	v_fma_f32 v68, |v230|, -v165, v68
	v_fma_f32 v69, |v231|, -v165, v69
	v_fma_f32 v70, |v232|, -v165, v70
	v_fma_f32 v71, |v233|, -v165, v71
	v_fma_f32 v72, |v234|, -v165, v72
	v_fma_f32 v73, |v235|, -v165, v73
	v_fma_f32 v74, |v236|, -v165, v74
	v_fma_f32 v75, |v237|, -v165, v75
	v_fma_f32 v76, |v242|, -v165, v76
	v_fma_f32 v77, |v243|, -v165, v77
	v_fma_f32 v78, |v244|, -v165, v78
	v_fma_f32 v79, |v245|, -v165, v79
	v_add_u32_e32 v211, s70, v226
	ds_read_b128 v[186:189], v211 offset:30848
	ds_read_b128 v[230:233], v211 offset:30880
	ds_read_b128 v[234:237], v211 offset:30912
	ds_read_b128 v[242:245], v211 offset:30944
	v_exp_f32_e32 v64, v64
	v_exp_f32_e32 v65, v65
	v_add_f32_e32 v184, v184, v64
	v_exp_f32_e32 v66, v66
	v_add_f32_e32 v184, v184, v65
	v_exp_f32_e32 v67, v67
	v_add_f32_e32 v184, v184, v66
	v_exp_f32_e32 v68, v68
	v_add_f32_e32 v184, v184, v67
	v_exp_f32_e32 v69, v69
	v_add_f32_e32 v184, v184, v68
	v_exp_f32_e32 v70, v70
	v_add_f32_e32 v184, v184, v69
	v_exp_f32_e32 v71, v71
	v_add_f32_e32 v184, v184, v70
	v_exp_f32_e32 v72, v72
	v_add_f32_e32 v184, v184, v71
	v_exp_f32_e32 v73, v73
	v_add_f32_e32 v184, v184, v72
	v_exp_f32_e32 v74, v74
	v_add_f32_e32 v184, v184, v73
	v_exp_f32_e32 v75, v75
	v_add_f32_e32 v184, v184, v74
	v_exp_f32_e32 v76, v76
	v_add_f32_e32 v184, v184, v75
	v_exp_f32_e32 v77, v77
	v_add_f32_e32 v184, v184, v76
	v_exp_f32_e32 v78, v78
	v_add_f32_e32 v184, v184, v77
	v_exp_f32_e32 v79, v79
	v_add_f32_e32 v184, v184, v78
	v_add_f32_e32 v184, v184, v79
	v_cvt_pk_bf16_f32 v64, v64, v65
	v_cvt_pk_bf16_f32 v65, v66, v67
	v_cvt_pk_bf16_f32 v66, v68, v69
	v_cvt_pk_bf16_f32 v67, v70, v71
	v_cvt_pk_bf16_f32 v68, v72, v73
	v_cvt_pk_bf16_f32 v69, v74, v75
	v_cvt_pk_bf16_f32 v70, v76, v77
	v_cvt_pk_bf16_f32 v71, v78, v79
	s_nop 1
	s_waitcnt lgkmcnt(15)
	v_mfma_f32_32x32x16_bf16 v[48:63], v[64:67], v[124:127], v[48:63]
	ds_read_b64_tr_b16 v[124:125], v209 offset:8192
	ds_read_b64_tr_b16 v[126:127], v209 offset:8448
	s_waitcnt lgkmcnt(2)
	v_sub_f32_e32 v186, v168, v186
	v_sub_f32_e32 v187, v168, v187
	v_sub_f32_e32 v188, v168, v188
	v_sub_f32_e32 v189, v168, v189
	v_sub_f32_e32 v230, v168, v230
	v_sub_f32_e32 v231, v168, v231
	v_sub_f32_e32 v232, v168, v232
	v_sub_f32_e32 v233, v168, v233
	s_waitcnt lgkmcnt(15)
	v_mfma_f32_32x32x16_bf16 v[32:47], v[64:67], v[128:131], v[32:47]
	ds_read_b64_tr_b16 v[128:129], v209 offset:8704
	ds_read_b64_tr_b16 v[130:131], v209 offset:8960
	v_sub_f32_e32 v234, v168, v234
	v_sub_f32_e32 v235, v168, v235
	v_sub_f32_e32 v236, v168, v236
	v_sub_f32_e32 v237, v168, v237
	v_sub_f32_e32 v242, v168, v242
	v_sub_f32_e32 v243, v168, v243
	v_sub_f32_e32 v244, v168, v244
	v_sub_f32_e32 v245, v168, v245
	v_fma_f32 v80, |v186|, -v165, v80
	v_fma_f32 v81, |v187|, -v165, v81
	s_waitcnt lgkmcnt(15)
	v_mfma_f32_32x32x16_bf16 v[16:31], v[64:67], v[132:135], v[16:31]
	ds_read_b64_tr_b16 v[132:133], v209 offset:9216
	ds_read_b64_tr_b16 v[134:135], v209 offset:9472
	v_fma_f32 v82, |v188|, -v165, v82
	v_fma_f32 v83, |v189|, -v165, v83
	v_fma_f32 v84, |v230|, -v165, v84
	v_fma_f32 v85, |v231|, -v165, v85
	v_fma_f32 v86, |v232|, -v165, v86
	v_fma_f32 v87, |v233|, -v165, v87
	v_fma_f32 v88, |v234|, -v165, v88
	v_fma_f32 v89, |v235|, -v165, v89
	v_fma_f32 v90, |v236|, -v165, v90
	v_fma_f32 v91, |v237|, -v165, v91
	s_waitcnt lgkmcnt(15)
	v_mfma_f32_32x32x16_bf16 v[0:15], v[64:67], v[136:139], v[0:15]
	ds_read_b64_tr_b16 v[136:137], v209 offset:9728
	ds_read_b64_tr_b16 v[138:139], v209 offset:9984
	v_fma_f32 v92, |v242|, -v165, v92
	v_fma_f32 v93, |v243|, -v165, v93
	v_fma_f32 v94, |v244|, -v165, v94
	v_fma_f32 v95, |v245|, -v165, v95
	v_exp_f32_e32 v80, v80
	v_exp_f32_e32 v81, v81
	v_add_f32_e32 v184, v184, v80
	v_exp_f32_e32 v82, v82
	v_add_f32_e32 v184, v184, v81
	v_exp_f32_e32 v83, v83
	s_andn2_b64 vcc, exec, s[16:17]
	s_cbranch_vccnz .Ld1_nostage
	s_sub_i32 s70, 0, s45
	v_add_u32_e32 v229, s70, v164
	s_waitcnt vmcnt(0)
	ds_write_b128 v229, v[104:107] offset:30976
	v_add_u32_e32 v229, s70, v219
	ds_write_b128 v229, v[108:111] offset:45312
	v_add_u32_e32 v229, s70, v220
	v_cvt_f32_i32_e32 v207, v207
	ds_write_b128 v229, v[120:123] offset:45312
	s_and_saveexec_b64 s[16:17], s[42:43]
	s_cbranch_execz .Ld1_stg_done
	v_add_u32_e32 v229, s70, v227
	ds_write_b32 v229, v207 offset:61696

; #define SBAR() __builtin_amdgcn_sched_barrier(0)
; #define SWRITED(boff) do { char* bb_ = lds + (boff); *reinterpret_cast<bf16x8*>(bb_ + KN_OFF + kn_st) = s_kn; *reinterpret_cast<bf16x8*>(bb_ + V_OFF + vst0) = s_v0; \
;     *reinterpret_cast<bf16x8*>(bb_ + V_OFF + vst1) = s_v1; if (tid < 64) *reinterpret_cast<float*>(bb_ + PK_OFF + tid * 4) = s_pk; } while (0)
; #define VRD(D0, L, H) do { constexpr int KS = 2 * 4 * 512, HF = 4 * 512, B0 = (D0) * 512; \
;             L[0] = tr_read<B0>(vb); H[0] = tr_read<B0 + HF>(vb); L[1] = tr_read<B0 + KS>(vb); H[1] = tr_read<B0 + KS + HF>(vb); \
;             L[2] = tr_read<B0 + 2 * KS>(vb); H[2] = tr_read<B0 + 2 * KS + HF>(vb); L[3] = tr_read<B0 + 3 * KS>(vb); H[3] = tr_read<B0 + 3 * KS + HF>(vb); } while (0)
; #define PVM(D0, L, H) do { o[D0] = __builtin_amdgcn_mfma_f32_32x32x16_bf16(fa0, VFR(L, H, 0), o[D0], 0, 0, 0); o[D0] = __builtin_amdgcn_mfma_f32_32x32x16_bf16(fa1, VFR(L, H, 1), o[D0], 0, 0, 0); \
;             o[D0] = __builtin_amdgcn_mfma_f32_32x32x16_bf16(fa2, VFR(L, H, 2), o[D0], 0, 0, 0); o[D0] = __builtin_amdgcn_mfma_f32_32x32x16_bf16(fa3, VFR(L, H, 3), o[D0], 0, 0, 0); } while (0)
; __device__ __forceinline__ void attn_diff1(const bf16* __restrict__ Qrow, const bf16* __restrict__ Kn, const bf16* __restrict__ Vh, const int* __restrict__ posk, const float pq, const float cneg, ...
;     ...
;         asm volatile("s_waitcnt lgkmcnt(0)" ::: "memory"); SBAR();
;         PVM(0, la, ha); SBAR();
;         VRD(2, la, ha);
;         SBAR(); PVM(1, lb, hb); SBAR();
;         VRD(3, lb, hb);
;         asm volatile("s_waitcnt lgkmcnt(8)" ::: "memory"); SBAR();
;         PVM(2, la, ha);
;         asm volatile("s_waitcnt lgkmcnt(0)" ::: "memory"); SBAR();
;         PVM(3, lb, hb);
;     ...
;         if (t + 1 < NT) SWRITED(BUF - cur);
;         __syncthreads();
;         cur = BUF - cur;
;     }
.Ld1_nostage:
	s_waitcnt lgkmcnt(15)
	v_mfma_f32_32x32x16_bf16 v[48:63], v[68:71], v[140:143], v[48:63]
	ds_read_b64_tr_b16 v[140:141], v209 offset:12288
	ds_read_b64_tr_b16 v[142:143], v209 offset:12544
	v_add_f32_e32 v184, v184, v82
	v_exp_f32_e32 v84, v84
	v_add_f32_e32 v184, v184, v83
	v_exp_f32_e32 v85, v85
	v_add_f32_e32 v184, v184, v84
	v_exp_f32_e32 v86, v86
	v_add_f32_e32 v184, v184, v85
	v_exp_f32_e32 v87, v87
	v_add_f32_e32 v184, v184, v86
	s_waitcnt lgkmcnt(15)
	v_mfma_f32_32x32x16_bf16 v[32:47], v[68:71], v[144:147], v[32:47]
	ds_read_b64_tr_b16 v[144:145], v209 offset:12800
	ds_read_b64_tr_b16 v[146:147], v209 offset:13056
	v_exp_f32_e32 v88, v88
	v_add_f32_e32 v184, v184, v87
	v_exp_f32_e32 v89, v89
	v_add_f32_e32 v184, v184, v88
	v_exp_f32_e32 v90, v90
	v_add_f32_e32 v184, v184, v89
	v_exp_f32_e32 v91, v91
	v_add_f32_e32 v184, v184, v90
	v_exp_f32_e32 v92, v92
	s_waitcnt lgkmcnt(15)
	v_mfma_f32_32x32x16_bf16 v[16:31], v[68:71], v[148:151], v[16:31]
	ds_read_b64_tr_b16 v[148:149], v209 offset:13312
	ds_read_b64_tr_b16 v[150:151], v209 offset:13568
	v_add_f32_e32 v184, v184, v91
	v_exp_f32_e32 v93, v93
	v_add_f32_e32 v184, v184, v92
	v_exp_f32_e32 v94, v94
	v_add_f32_e32 v184, v184, v93
	v_exp_f32_e32 v95, v95
	v_add_f32_e32 v184, v184, v94
	v_add_f32_e32 v184, v184, v95
	v_cvt_pk_bf16_f32 v80, v80, v81
	s_waitcnt lgkmcnt(15)
	v_mfma_f32_32x32x16_bf16 v[0:15], v[68:71], v[152:155], v[0:15]
	ds_read_b64_tr_b16 v[152:153], v209 offset:13824
	ds_read_b64_tr_b16 v[154:155], v209 offset:14080
	v_cvt_pk_bf16_f32 v81, v82, v83
	v_cvt_pk_bf16_f32 v82, v84, v85
	v_cvt_pk_bf16_f32 v83, v86, v87
	v_cvt_pk_bf16_f32 v84, v88, v89
	v_cvt_pk_bf16_f32 v85, v90, v91
	v_cvt_pk_bf16_f32 v86, v92, v93
	v_cvt_pk_bf16_f32 v87, v94, v95
	s_nop 1
	s_waitcnt lgkmcnt(14)
	v_mfma_f32_32x32x16_bf16 v[48:63], v[80:83], v[124:127], v[48:63]
	s_waitcnt lgkmcnt(12)
	v_mfma_f32_32x32x16_bf16 v[32:47], v[80:83], v[128:131], v[32:47]
	s_waitcnt lgkmcnt(10)
	v_mfma_f32_32x32x16_bf16 v[16:31], v[80:83], v[132:135], v[16:31]
	s_waitcnt lgkmcnt(8)
	v_mfma_f32_32x32x16_bf16 v[0:15], v[80:83], v[136:139], v[0:15]
	s_waitcnt lgkmcnt(0)
	s_barrier
	v_mfma_f32_32x32x16_bf16 v[48:63], v[84:87], v[140:143], v[48:63]
	v_mfma_f32_32x32x16_bf16 v[32:47], v[84:87], v[144:147], v[32:47]
	v_mfma_f32_32x32x16_bf16 v[16:31], v[84:87], v[148:151], v[16:31]
	v_mfma_f32_32x32x16_bf16 v[0:15], v[84:87], v[152:155], v[0:15]
	s_sub_i32 s45, 0x7900, s45
	s_add_i32 s69, s69, 1
	v_add_u32_e32 v206, 64, v206
	v_add_u32_e32 v208, 64, v208
	v_add_u32_e32 v210, 64, v210
	s_cmp_eq_u32 s54, s69
	s_cbranch_scc1 .LBB0_537
	s_branch .LBB0_531

; #define SBAR() __builtin_amdgcn_sched_barrier(0)
; #define SLOAD2(k0) do { s_kn = *reinterpret_cast<const bf16x8*>(Kn + (size_t)((k0) + kn_r) * 1024 + kn_c); s_kr = *reinterpret_cast<const bf16x8*>(Kr + (size_t)((k0) + kr_r) * 32 + kr_c); \
;     s_v = *reinterpret_cast<const bf16x8*>(Vh + (size_t)((k0) + kn_r) * 1024 + kn_c); } while (0)
; __device__ __forceinline__ void attn_mla2(const bf16* __restrict__ Q0, const bf16* __restrict__ Q1, const bf16* __restrict__ Kn, const bf16* __restrict__ Kr, const bf16* __restrict__ Vh, ...
;     ...
;     for (int t = 0; t < NT; ++t) {
;         const char* buf = lds + cur;
;         f32x16 pa0 = f32x16{}, pa1 = f32x16{}, pb0 = f32x16{}, pb1 = f32x16{};
;         {
;             const char* kb = buf + KN_OFF + r32 * 144 + hi * 16; const char* kr = buf + KR_OFF + r32 * 80 + hi * 16;
;     ...
;             bf16x8 c0 = KLD0(0), c1 = KLD1(0);
; #pragma unroll
;             for (int d0 = 0; d0 < 6; ++d0) {
;                 bf16x8 n0 = c0, n1 = c1;
;                 if (d0 + 1 < 6) { n0 = KLD0(d0 + 1); n1 = KLD1(d0 + 1); }
;                 pa0 = __builtin_amdgcn_mfma_f32_32x32x16_bf16(c0, q0[d0], pa0, 0, 0, 0); pb0 = __builtin_amdgcn_mfma_f32_32x32x16_bf16(c0, q1[d0], pb0, 0, 0, 0);
;                 pa1 = __builtin_amdgcn_mfma_f32_32x32x16_bf16(c1, q0[d0], pa1, 0, 0, 0); pb1 = __builtin_amdgcn_mfma_f32_32x32x16_bf16(c1, q1[d0], pb1, 0, 0, 0);
;                 SBAR(); c0 = n0; c1 = n1;
;             }
;     ...
;         }
;         if (t + 1 < NT) SLOAD2((t + 1) * 64);
;         bf16x8 fa0, fa1, fa2, fa3, fb0, fb1, fb2, fb3;
;         {   float ps = 0.f;
; #pragma unroll
;             for (int r = 0; r < 16; ++r) { pa0[r] = __builtin_amdgcn_exp2f(pa0[r]); pa1[r] = __builtin_amdgcn_exp2f(pa1[r]);     ps += pa0[r] + pa1[r]; }
;             l0 += ps; PK4(pa0, 0, fa0); PK4(pa0, 8, fa1); PK4(pa1, 0, fa2); PK4(pa1, 8, fa3); }
;         {   float ps = 0.f;
; #pragma unroll
;             for (int r = 0; r < 16; ++r) { pb0[r] = __builtin_amdgcn_exp2f(pb0[r]); pb1[r] = __builtin_amdgcn_exp2f(pb1[r]); ps += pb0[r] + pb1[r]; }
;             l1 += ps; PK4(pb0, 0, fb0); PK4(pb0, 8, fb1); PK4(pb1, 0, fb2); PK4(pb1, 8, fb3); }
.LBB0_1629:
	s_add_i32 s12, s16, 0
	v_add3_u32 v184, s12, v246, v244
	v_add3_u32 v188, s12, v245, v244
	ds_read_b128 v[196:199], v184
	ds_read_b128 v[200:203], v184 offset:32
	ds_read_b128 v[204:207], v184 offset:64
	ds_read_b128 v[208:211], v184 offset:96
	ds_read_b128 v[212:215], v188 offset:9216
	ds_read_b128 v[216:219], v188 offset:9248
	ds_read_b128 v[220:223], v184 offset:4608
	ds_read_b128 v[224:227], v184 offset:4640
	ds_read_b128 v[228:231], v184 offset:4672
	ds_read_b128 v[232:235], v184 offset:4704
	ds_read_b128 v[236:239], v188 offset:11776
	ds_read_b128 v[250:253], v188 offset:11808
	v_lshl_add_u64 v[176:177], v[194:195], 0, s[2:3]
	s_mov_b32 s12, 0x8e20000
	v_add_co_u32_e32 v178, vcc, s12, v176
	s_mov_b32 s12, 0xae20000
	s_nop 0
	v_addc_co_u32_e32 v179, vcc, 0, v177, vcc
	v_add_co_u32_e32 v176, vcc, s12, v176
	s_nop 1
	v_addc_co_u32_e32 v177, vcc, 0, v177, vcc
	global_load_dwordx4 v[180:183], v[178:179], off
	global_load_dwordx4 v[176:179], v[176:177], off
	v_lshl_add_u64 v[186:187], v[192:193], 0, s[2:3]
	global_load_dwordx2 v[186:187], v[186:187], off
	s_waitcnt lgkmcnt(11)
	v_mfma_f32_32x32x16_bf16 v[96:111], v[196:199], v[160:163], 0
	s_sub_i32 s15, 0, s16
	v_ashrrev_i32_e32 v64, 3, v241
	v_and_b32_e32 v65, 7, v241
	v_lshlrev_b32_e32 v66, 4, v65
	v_mul_u32_u24_e32 v184, 0x90, v64
	v_add_f32_e32 v190, v190, v112
	v_add_f32_e32 v191, v191, v80
	v_add_f32_e32 v190, v190, v113
	v_add_f32_e32 v191, v191, v81
	s_waitcnt lgkmcnt(10)
	v_mfma_f32_32x32x16_bf16 v[96:111], v[200:203], v[168:171], v[96:111]
	v_add3_u32 v184, s15, v184, v66
	v_mul_u32_u24_e32 v189, 0x50, v64
	v_lshlrev_b32_e32 v67, 3, v65
	v_add3_u32 v189, s15, v189, v67
	v_add_f32_e32 v190, v190, v114
	v_add_f32_e32 v191, v191, v82
	v_add_f32_e32 v190, v190, v115
	v_add_f32_e32 v191, v191, v83
	s_waitcnt lgkmcnt(9)
	v_mfma_f32_32x32x16_bf16 v[96:111], v[204:207], v[156:159], v[96:111]
	v_bfe_u32 v67, v241, 3, 2
	v_and_b32_e32 v66, 48, v66
	v_lshlrev_b32_e32 v68, 1, v64
	v_and_b32_e32 v69, 0x1fffff0, v64
	v_add_f32_e32 v190, v190, v116
	v_add_f32_e32 v191, v191, v84
	v_add_f32_e32 v190, v190, v117
	v_add_f32_e32 v191, v191, v85
	s_waitcnt lgkmcnt(8)
	v_mfma_f32_32x32x16_bf16 v[96:111], v[208:211], v[144:147], v[96:111]
	v_and_b32_e32 v68, 8, v68
	v_or3_b32 v65, v68, v69, v65
	v_lshrrev_b32_e32 v64, 1, v64
	v_lshlrev_b32_e32 v65, 7, v65
	v_add_f32_e32 v190, v190, v118
	v_add_f32_e32 v191, v191, v86
	v_add_f32_e32 v190, v190, v119
	v_add_f32_e32 v191, v191, v87
	s_waitcnt lgkmcnt(7)
	v_mfma_f32_32x32x16_bf16 v[96:111], v[212:215], v[140:143], v[96:111]
	v_and_b32_e32 v65, 0xfffffe00, v65
	v_and_or_b32 v67, v64, 4, v67
	v_lshlrev_b32_e32 v67, 6, v67
	v_add_u32_e32 v64, s15, v65
	v_add_f32_e32 v190, v190, v120
	v_add_f32_e32 v191, v191, v88
	v_add_f32_e32 v190, v190, v121
	v_add_f32_e32 v191, v191, v89
	s_waitcnt lgkmcnt(6)
	v_mfma_f32_32x32x16_bf16 v[96:111], v[216:219], v[128:131], v[96:111]
	v_add3_u32 v188, v64, v67, v66
	v_lshl_add_u64 v[192:193], v[192:193], 0, s[30:31]
	v_lshl_add_u64 v[194:195], v[194:195], 0, s[36:37]
	s_nop 0
	v_add_f32_e32 v190, v190, v122
	v_add_f32_e32 v191, v191, v90
	v_add_f32_e32 v190, v190, v123
	v_add_f32_e32 v191, v191, v91
	v_mfma_f32_32x32x16_bf16 v[64:79], v[196:199], v[164:167], 0
	v_add_f32_e32 v190, v190, v124
	v_add_f32_e32 v191, v191, v92
	v_add_f32_e32 v190, v190, v125
	v_add_f32_e32 v191, v191, v93
	v_add_f32_e32 v190, v190, v126
	v_add_f32_e32 v191, v191, v94
	v_add_f32_e32 v190, v190, v127
	v_add_f32_e32 v191, v191, v95
	v_mfma_f32_32x32x16_bf16 v[64:79], v[200:203], v[172:175], v[64:79]
	v_exp_f32_e32 v96, v96
	v_exp_f32_e32 v97, v97
	v_add_f32_e32 v190, v190, v96
	v_exp_f32_e32 v98, v98
	v_add_f32_e32 v190, v190, v97
	v_mfma_f32_32x32x16_bf16 v[64:79], v[204:207], v[152:155], v[64:79]
	v_exp_f32_e32 v99, v99
	v_add_f32_e32 v190, v190, v98
	v_exp_f32_e32 v100, v100
	v_add_f32_e32 v190, v190, v99
	v_exp_f32_e32 v101, v101
	v_mfma_f32_32x32x16_bf16 v[64:79], v[208:211], v[148:151], v[64:79]
	v_add_f32_e32 v190, v190, v100
	v_exp_f32_e32 v102, v102
	v_add_f32_e32 v190, v190, v101
	v_exp_f32_e32 v103, v103
	v_add_f32_e32 v190, v190, v102
	v_exp_f32_e32 v104, v104
	v_mfma_f32_32x32x16_bf16 v[64:79], v[212:215], v[136:139], v[64:79]
	v_add_f32_e32 v190, v190, v103
	v_exp_f32_e32 v105, v105
	v_add_f32_e32 v190, v190, v104
	v_exp_f32_e32 v106, v106
	v_add_f32_e32 v190, v190, v105
	v_mfma_f32_32x32x16_bf16 v[64:79], v[216:219], v[132:135], v[64:79]
	v_exp_f32_e32 v107, v107
	v_add_f32_e32 v190, v190, v106
	v_exp_f32_e32 v108, v108
	v_add_f32_e32 v190, v190, v107
	v_exp_f32_e32 v109, v109
	v_and_b32_e32 v213, 32, v241
	v_mad_u32_u24 v212, v213, 24, v248
	v_add_u32_e32 v212, s16, v212
	s_waitcnt lgkmcnt(5)
	v_mfma_f32_32x32x16_bf16 v[112:127], v[220:223], v[160:163], 0
	v_add_f32_e32 v190, v190, v108
	v_exp_f32_e32 v110, v110
	v_add_f32_e32 v190, v190, v109
	v_exp_f32_e32 v111, v111
	v_add_f32_e32 v190, v190, v110
	v_add_f32_e32 v190, v190, v111
	s_waitcnt lgkmcnt(4)
	v_mfma_f32_32x32x16_bf16 v[112:127], v[224:227], v[168:171], v[112:127]
	v_exp_f32_e32 v64, v64
	v_exp_f32_e32 v65, v65
	v_add_f32_e32 v191, v191, v64
	v_exp_f32_e32 v66, v66
	v_add_f32_e32 v191, v191, v65
	s_waitcnt lgkmcnt(3)
	v_mfma_f32_32x32x16_bf16 v[112:127], v[228:231], v[156:159], v[112:127]
	v_exp_f32_e32 v67, v67
	v_add_f32_e32 v191, v191, v66
	v_exp_f32_e32 v68, v68
	v_add_f32_e32 v191, v191, v67
	v_exp_f32_e32 v69, v69
	s_waitcnt lgkmcnt(2)
; template <int DVB> __device__ __forceinline__ int v_st(int k, int c) { const int kk = (k & ~0xC) | ((k & 4) << 1) | ((k & 8) >> 1); return ((kk >> 3) * DVB + (c >> 5)) * 512 + ((kk & 7) * 32 + (c & 31)) * 2; }
; __device__ __forceinline__ void attn_mla2(const bf16* __restrict__ Q0, const bf16* __restrict__ Q1, const bf16* __restrict__ Kn, const bf16* __restrict__ Kr, const bf16* __restrict__ Vh, ...
;     ...
;         {   float ps = 0.f;
; #pragma unroll
;             for (int r = 0; r < 16; ++r) { pa0[r] = __builtin_amdgcn_exp2f(pa0[r]); pa1[r] = __builtin_amdgcn_exp2f(pa1[r]);     ps += pa0[r] + pa1[r]; }
;             l0 += ps; PK4(pa0, 0, fa0); PK4(pa0, 8, fa1); PK4(pa1, 0, fa2); PK4(pa1, 8, fa3); }
;         {   float ps = 0.f;
; #pragma unroll
;             for (int r = 0; r < 16; ++r) { pb0[r] = __builtin_amdgcn_exp2f(pb0[r]); pb1[r] = __builtin_amdgcn_exp2f(pb1[r]); ps += pb0[r] + pb1[r]; }
;             l1 += ps; PK4(pb0, 0, fb0); PK4(pb0, 8, fb1); PK4(pb1, 0, fb2); PK4(pb1, 8, fb3); }
;         {   const int vb = vb0 + cur;
;     ...
;             PV2(0); PV2(1);
;     ...
;         }
;         if (t + 1 < NT) {
;             int tw = tid; asm volatile("" : "+v"(tw));
;             char* bb_ = lds + (BUF - cur);
;             *reinterpret_cast<bf16x8*>(bb_ + KN_OFF + (tw >> 3) * 144 + (tw & 7) * 16) = s_kn;
;             if (tw < 256) *reinterpret_cast<bf16x8*>(bb_ + KR_OFF + ((tw >> 2) & 63) * 80 + (tw & 3) * 16) = s_kr;
;             *reinterpret_cast<bf16x8*>(bb_ + V_OFF + v_st<2>(tw >> 3, (tw & 7) * 8)) = s_v;
;         }
;         __syncthreads();
;         cur = BUF - cur;
	v_mfma_f32_32x32x16_bf16 v[112:127], v[232:235], v[144:147], v[112:127]
	v_add_f32_e32 v191, v191, v68
	v_exp_f32_e32 v70, v70
	v_add_f32_e32 v191, v191, v69
	v_exp_f32_e32 v71, v71
	v_add_f32_e32 v191, v191, v70
	v_exp_f32_e32 v72, v72
	s_waitcnt lgkmcnt(1)
	v_mfma_f32_32x32x16_bf16 v[112:127], v[236:239], v[140:143], v[112:127]
	v_add_f32_e32 v191, v191, v71
	v_exp_f32_e32 v73, v73
	v_add_f32_e32 v191, v191, v72
	v_exp_f32_e32 v74, v74
	v_add_f32_e32 v191, v191, v73
	s_waitcnt lgkmcnt(0)
	v_mfma_f32_32x32x16_bf16 v[112:127], v[250:253], v[128:131], v[112:127]
	v_exp_f32_e32 v75, v75
	v_add_f32_e32 v191, v191, v74
	v_exp_f32_e32 v76, v76
	v_add_f32_e32 v191, v191, v75
	v_exp_f32_e32 v77, v77
	v_mfma_f32_32x32x16_bf16 v[80:95], v[220:223], v[164:167], 0
	v_add_f32_e32 v191, v191, v76
	v_exp_f32_e32 v78, v78
	v_add_f32_e32 v191, v191, v77
	v_exp_f32_e32 v79, v79
	v_add_f32_e32 v191, v191, v78
	v_add_f32_e32 v191, v191, v79
	v_mfma_f32_32x32x16_bf16 v[80:95], v[224:227], v[172:175], v[80:95]
	v_cvt_pk_bf16_f32 v196, v96, v97
	v_cvt_pk_bf16_f32 v197, v98, v99
	v_cvt_pk_bf16_f32 v198, v100, v101
	v_cvt_pk_bf16_f32 v199, v102, v103
	v_cvt_pk_bf16_f32 v200, v104, v105
	v_cvt_pk_bf16_f32 v201, v106, v107
	v_cvt_pk_bf16_f32 v202, v108, v109
	v_cvt_pk_bf16_f32 v203, v110, v111
	v_mfma_f32_32x32x16_bf16 v[80:95], v[228:231], v[152:155], v[80:95]
	ds_read_b64_tr_b16 v[96:97], v212 offset:0
	ds_read_b64_tr_b16 v[98:99], v212 offset:256
	ds_read_b64_tr_b16 v[100:101], v212 offset:2048
	ds_read_b64_tr_b16 v[102:103], v212 offset:2304
	ds_read_b64_tr_b16 v[104:105], v212 offset:512
	ds_read_b64_tr_b16 v[106:107], v212 offset:768
	ds_read_b64_tr_b16 v[108:109], v212 offset:2560
	ds_read_b64_tr_b16 v[110:111], v212 offset:2816
	v_mfma_f32_32x32x16_bf16 v[80:95], v[232:235], v[148:151], v[80:95]
	v_cvt_pk_bf16_f32 v204, v64, v65
	v_cvt_pk_bf16_f32 v205, v66, v67
	v_cvt_pk_bf16_f32 v206, v68, v69
	v_cvt_pk_bf16_f32 v207, v70, v71
	v_cvt_pk_bf16_f32 v208, v72, v73
	v_cvt_pk_bf16_f32 v209, v74, v75
	v_cvt_pk_bf16_f32 v210, v76, v77
	v_cvt_pk_bf16_f32 v211, v78, v79
	v_mfma_f32_32x32x16_bf16 v[80:95], v[236:239], v[136:139], v[80:95]
	ds_read_b64_tr_b16 v[64:65], v212 offset:4096
	ds_read_b64_tr_b16 v[66:67], v212 offset:4352
	ds_read_b64_tr_b16 v[68:69], v212 offset:6144
	ds_read_b64_tr_b16 v[70:71], v212 offset:6400
	ds_read_b64_tr_b16 v[72:73], v212 offset:4608
	ds_read_b64_tr_b16 v[74:75], v212 offset:4864
	ds_read_b64_tr_b16 v[76:77], v212 offset:6656
	ds_read_b64_tr_b16 v[78:79], v212 offset:6912
	v_mfma_f32_32x32x16_bf16 v[80:95], v[250:253], v[132:135], v[80:95]
	v_exp_f32_e32 v112, v112
	v_exp_f32_e32 v113, v113
	v_exp_f32_e32 v114, v114
	s_waitcnt lgkmcnt(8)
	v_mfma_f32_32x32x16_bf16 v[0:15], v[196:199], v[96:99], v[0:15]
	v_exp_f32_e32 v115, v115
	v_exp_f32_e32 v116, v116
	v_exp_f32_e32 v117, v117
	v_mfma_f32_32x32x16_bf16 v[32:47], v[204:207], v[96:99], v[32:47]
	v_exp_f32_e32 v118, v118
	v_exp_f32_e32 v119, v119
	v_exp_f32_e32 v120, v120
	v_mfma_f32_32x32x16_bf16 v[16:31], v[196:199], v[104:107], v[16:31]
	v_exp_f32_e32 v121, v121
	v_exp_f32_e32 v122, v122
	v_exp_f32_e32 v123, v123
	v_mfma_f32_32x32x16_bf16 v[48:63], v[204:207], v[104:107], v[48:63]
	v_exp_f32_e32 v124, v124
	v_exp_f32_e32 v125, v125
	v_mfma_f32_32x32x16_bf16 v[0:15], v[200:203], v[100:103], v[0:15]
	v_exp_f32_e32 v126, v126
	v_exp_f32_e32 v127, v127
	s_waitcnt vmcnt(0)
	ds_write_b128 v184, v[180:183] offset:30976
	ds_write_b128 v188, v[176:179] offset:45312
	ds_write_b64 v189, v[186:187] offset:40192
	v_mfma_f32_32x32x16_bf16 v[32:47], v[208:211], v[100:103], v[32:47]
	v_cvt_pk_bf16_f32 v220, v112, v113
	v_cvt_pk_bf16_f32 v221, v114, v115
	v_cvt_pk_bf16_f32 v222, v116, v117
	v_cvt_pk_bf16_f32 v223, v118, v119
	v_cvt_pk_bf16_f32 v224, v120, v121
	v_cvt_pk_bf16_f32 v225, v122, v123
	v_cvt_pk_bf16_f32 v226, v124, v125
	v_cvt_pk_bf16_f32 v227, v126, v127
	v_mfma_f32_32x32x16_bf16 v[16:31], v[200:203], v[108:111], v[16:31]
	v_exp_f32_e32 v80, v80
	v_exp_f32_e32 v81, v81
	v_exp_f32_e32 v82, v82
	v_mfma_f32_32x32x16_bf16 v[48:63], v[208:211], v[108:111], v[48:63]
	v_exp_f32_e32 v83, v83
	v_exp_f32_e32 v84, v84
	v_exp_f32_e32 v85, v85
	s_waitcnt lgkmcnt(0)
	v_mfma_f32_32x32x16_bf16 v[0:15], v[220:223], v[64:67], v[0:15]
	v_exp_f32_e32 v86, v86
	v_exp_f32_e32 v87, v87
	v_exp_f32_e32 v88, v88
	v_mfma_f32_32x32x16_bf16 v[16:31], v[220:223], v[72:75], v[16:31]
	v_exp_f32_e32 v89, v89
	v_exp_f32_e32 v90, v90
	v_exp_f32_e32 v91, v91
	v_mfma_f32_32x32x16_bf16 v[0:15], v[224:227], v[68:71], v[0:15]
	v_exp_f32_e32 v92, v92
	v_exp_f32_e32 v93, v93
	v_mfma_f32_32x32x16_bf16 v[16:31], v[224:227], v[76:79], v[16:31]
	v_exp_f32_e32 v94, v94
	v_exp_f32_e32 v95, v95
	v_cvt_pk_bf16_f32 v228, v80, v81
	v_cvt_pk_bf16_f32 v229, v82, v83
	v_cvt_pk_bf16_f32 v230, v84, v85
	v_cvt_pk_bf16_f32 v231, v86, v87
	v_cvt_pk_bf16_f32 v232, v88, v89
	v_cvt_pk_bf16_f32 v233, v90, v91
	v_cvt_pk_bf16_f32 v234, v92, v93
	v_cvt_pk_bf16_f32 v235, v94, v95
	s_sub_i32 s16, 0x7900, s16
	s_add_i32 s14, s14, -1
	s_cmp_eq_u32 s14, 0
	s_barrier
	v_mfma_f32_32x32x16_bf16 v[32:47], v[228:231], v[64:67], v[32:47]
	v_mfma_f32_32x32x16_bf16 v[48:63], v[228:231], v[72:75], v[48:63]
	v_mfma_f32_32x32x16_bf16 v[32:47], v[232:235], v[68:71], v[32:47]
	v_mfma_f32_32x32x16_bf16 v[48:63], v[232:235], v[76:79], v[48:63]
	s_cbranch_scc1 .Lmla_flush
	v_mov_b32_e32 v240, 0x358637bd
	s_branch .LBB0_1629
